# RES epilogue (phases 4,7): per-tile hoisted loads, merged gate loads, counted waits
# speedup vs baseline: 1.0109x; 1.0109x over previous
.LBB0_378:
	s_lshl_b32 s24, s61, 8
	s_add_i32 s70, s24, s37
	s_lshl_b64 s[2:3], s[2:3], s78
	s_lshl_b64 s[76:77], s[76:77], 10
	s_add_u32 s2, s76, s2
	s_addc_u32 s3, s77, s3
	s_lshl_b64 s[2:3], s[2:3], 2
	s_add_u32 s24, s74, s2
	s_addc_u32 s75, s75, s3
	s_ashr_i32 s71, s70, 31
	s_lshl_b64 s[70:71], s[70:71], 2
	s_add_u32 s74, s24, s70
	s_addc_u32 s75, s75, s71
	s_add_u32 s2, s72, s2
	s_addc_u32 s3, s73, s3
	s_add_u32 s2, s2, s70
	s_addc_u32 s3, s3, s71
	s_add_u32 s24, s20, s62
	s_addc_u32 s63, s21, s63
	s_add_u32 s62, s24, s70
	s_addc_u32 s63, s63, s71
	s_waitcnt lgkmcnt(5)
	v_lshl_add_u64 v[148:149], s[62:63], 0, v[178:179]
	s_mov_b64 s[62:63], 0x2000
	v_lshl_add_u64 v[132:133], s[2:3], 0, v[178:179]
	s_movk_i32 s2, 0x2000
	s_waitcnt lgkmcnt(4)
	v_lshl_add_u64 v[128:129], v[148:149], 0, s[62:63]
	v_add_co_u32_e32 v134, vcc, s2, v148
	v_lshl_add_u64 v[130:131], s[74:75], 0, v[178:179]
	ds_write_b128 v211, v[112:115]
	ds_write_b128 v211, v[116:119] offset:32
	ds_write_b128 v211, v[120:123] offset:64
	ds_write_b128 v211, v[124:127] offset:96
	v_mov_b32_e32 v185, v179
	v_addc_co_u32_e32 v135, vcc, 0, v149, vcc
	v_lshl_add_u64 v[114:115], v[130:131], 0, v[184:185]
	ds_read_b128 v[150:153], v212
	global_load_dwordx4 v[154:157], v[134:135], off
	global_load_dwordx4 v[158:161], v[114:115], off
	v_lshl_add_u64 v[112:113], v[132:133], 0, v[184:185]
	v_mov_b32_e32 v187, v179
	v_mov_b32_e32 v189, v179
	v_mov_b32_e32 v191, v179
	s_mov_b64 s[2:3], 0x20080
	s_add_i32 s65, s65, 1
	s_cmp_eq_u32 s65, s35
	ds_read_b128 v[162:165], v213
	s_nop 0
	v_lshl_add_u64 v[118:119], v[130:131], 0, v[186:187]
	global_load_dwordx4 v[166:169], v[118:119], off
	v_lshl_add_u64 v[116:117], v[132:133], 0, v[186:187]
	ds_read_b128 v[170:173], v214
	s_nop 0
	v_lshl_add_u64 v[122:123], v[130:131], 0, v[188:189]
	global_load_dwordx4 v[216:219], v[122:123], off
	v_lshl_add_u64 v[120:121], v[132:133], 0, v[188:189]
	ds_read_b128 v[220:223], v215
	s_nop 0
	v_lshl_add_u64 v[126:127], v[130:131], 0, v[190:191]
	global_load_dwordx4 v[224:227], v[126:127], off
	v_lshl_add_u64 v[124:125], v[132:133], 0, v[190:191]
	s_waitcnt vmcnt(3) lgkmcnt(3)
	v_pk_fma_f32 v[150:151], v[150:151], v[154:155], v[158:159]
	v_pk_fma_f32 v[152:153], v[152:153], v[156:157], v[160:161]
	global_store_dwordx4 v[112:113], v[150:153], off
	s_waitcnt vmcnt(3) lgkmcnt(2)
	v_pk_fma_f32 v[162:163], v[162:163], v[154:155], v[166:167]
	v_pk_fma_f32 v[164:165], v[164:165], v[156:157], v[168:169]
	global_store_dwordx4 v[116:117], v[162:165], off
	s_waitcnt vmcnt(3) lgkmcnt(1)
	v_pk_fma_f32 v[170:171], v[170:171], v[154:155], v[216:217]
	v_pk_fma_f32 v[172:173], v[172:173], v[156:157], v[218:219]
	global_store_dwordx4 v[120:121], v[170:173], off
	s_waitcnt vmcnt(3) lgkmcnt(0)
	v_pk_fma_f32 v[220:221], v[220:221], v[154:155], v[224:225]
	v_pk_fma_f32 v[222:223], v[222:223], v[156:157], v[226:227]
	global_store_dwordx4 v[124:125], v[220:223], off
	s_nop 1
	ds_write_b128 v211, v[96:99]
	ds_write_b128 v211, v[100:103] offset:32
	ds_write_b128 v211, v[104:107] offset:64
	ds_write_b128 v211, v[108:111] offset:96
	v_lshl_add_u64 v[148:149], v[130:131], 0, s[8:9]
	v_lshl_add_u64 v[150:151], v[148:149], 0, v[184:185]
	ds_read_b128 v[152:155], v212
	global_load_dwordx4 v[156:159], v[134:135], off
	s_nop 0
	global_load_dwordx4 v[160:163], v[150:151], off
	v_lshl_add_u64 v[164:165], v[132:133], 0, s[8:9]
	v_lshl_add_u64 v[166:167], v[164:165], 0, v[184:185]
	v_lshl_add_u64 v[168:169], v[148:149], 0, v[186:187]
	ds_read_b128 v[170:173], v213
	s_nop 0
	global_load_dwordx4 v[216:219], v[168:169], off
	v_lshl_add_u64 v[174:175], v[164:165], 0, v[186:187]
	v_lshl_add_u64 v[220:221], v[148:149], 0, v[188:189]
	ds_read_b128 v[222:225], v214
	s_nop 0
	global_load_dwordx4 v[240:243], v[220:221], off
	v_lshl_add_u64 v[226:227], v[164:165], 0, v[188:189]
	v_lshl_add_u64 v[244:245], v[148:149], 0, v[190:191]
	ds_read_b128 v[246:249], v215
	s_nop 0
	global_load_dwordx4 v[250:253], v[244:245], off
	v_lshl_add_u64 v[254:255], v[164:165], 0, v[190:191]
	s_waitcnt vmcnt(3) lgkmcnt(3)
	v_pk_fma_f32 v[152:153], v[152:153], v[156:157], v[160:161]
	v_pk_fma_f32 v[154:155], v[154:155], v[158:159], v[162:163]
	global_store_dwordx4 v[166:167], v[152:155], off
	s_waitcnt vmcnt(3) lgkmcnt(2)
	v_pk_fma_f32 v[170:171], v[170:171], v[156:157], v[216:217]
	v_pk_fma_f32 v[172:173], v[172:173], v[158:159], v[218:219]
	global_store_dwordx4 v[174:175], v[170:173], off
	s_waitcnt vmcnt(3) lgkmcnt(1)
	v_pk_fma_f32 v[222:223], v[222:223], v[156:157], v[240:241]
	v_pk_fma_f32 v[224:225], v[224:225], v[158:159], v[242:243]
	global_store_dwordx4 v[226:227], v[222:225], off
	s_waitcnt vmcnt(3) lgkmcnt(0)
	v_pk_fma_f32 v[246:247], v[246:247], v[156:157], v[250:251]
	v_pk_fma_f32 v[248:249], v[248:249], v[158:159], v[252:253]
	global_store_dwordx4 v[254:255], v[246:249], off
	s_nop 1
	ds_write_b128 v211, v[80:83]
	ds_write_b128 v211, v[84:87] offset:32
	ds_write_b128 v211, v[88:91] offset:64
	ds_write_b128 v211, v[92:95] offset:96
	ds_read_b128 v[148:151], v212
	global_load_dwordx4 v[152:155], v[128:129], off offset:128
	global_load_dwordx4 v[156:159], v[114:115], off offset:128
	ds_read_b128 v[160:163], v213
	global_load_dwordx4 v[164:167], v[118:119], off offset:128
	ds_read_b128 v[168:171], v214
	global_load_dwordx4 v[172:175], v[122:123], off offset:128
	ds_read_b128 v[216:219], v215
	global_load_dwordx4 v[220:223], v[126:127], off offset:128
	s_waitcnt vmcnt(3) lgkmcnt(3)
	v_pk_fma_f32 v[148:149], v[148:149], v[152:153], v[156:157]
	v_pk_fma_f32 v[150:151], v[150:151], v[154:155], v[158:159]
	global_store_dwordx4 v[112:113], v[148:151], off offset:128
	s_waitcnt vmcnt(3) lgkmcnt(2)
	v_pk_fma_f32 v[160:161], v[160:161], v[152:153], v[164:165]
	v_pk_fma_f32 v[162:163], v[162:163], v[154:155], v[166:167]
	global_store_dwordx4 v[116:117], v[160:163], off offset:128
	s_waitcnt vmcnt(3) lgkmcnt(1)
	v_pk_fma_f32 v[168:169], v[168:169], v[152:153], v[172:173]
	v_pk_fma_f32 v[170:171], v[170:171], v[154:155], v[174:175]
	global_store_dwordx4 v[120:121], v[168:171], off offset:128
	s_waitcnt vmcnt(3) lgkmcnt(0)
	v_pk_fma_f32 v[216:217], v[216:217], v[152:153], v[220:221]
	v_pk_fma_f32 v[218:219], v[218:219], v[154:155], v[222:223]
	global_store_dwordx4 v[124:125], v[216:219], off offset:128
	s_nop 1
	ds_write_b128 v211, v[64:67]
	ds_write_b128 v211, v[68:71] offset:32
	ds_write_b128 v211, v[72:75] offset:64
	ds_write_b128 v211, v[76:79] offset:96
	v_lshl_add_u64 v[148:149], v[130:131], 0, s[2:3]
	v_lshl_add_u64 v[150:151], v[148:149], 0, v[184:185]
	ds_read_b128 v[152:155], v212
	global_load_dwordx4 v[156:159], v[128:129], off offset:128
	s_nop 0
	global_load_dwordx4 v[160:163], v[150:151], off
	v_lshl_add_u64 v[164:165], v[132:133], 0, s[2:3]
	v_lshl_add_u64 v[166:167], v[164:165], 0, v[184:185]
	v_lshl_add_u64 v[168:169], v[148:149], 0, v[186:187]
	ds_read_b128 v[170:173], v213
	s_nop 0
	global_load_dwordx4 v[216:219], v[168:169], off
	v_lshl_add_u64 v[174:175], v[164:165], 0, v[186:187]
	v_lshl_add_u64 v[220:221], v[148:149], 0, v[188:189]
	ds_read_b128 v[222:225], v214
	s_nop 0
	global_load_dwordx4 v[240:243], v[220:221], off
	v_lshl_add_u64 v[226:227], v[164:165], 0, v[188:189]
	v_lshl_add_u64 v[244:245], v[148:149], 0, v[190:191]
	ds_read_b128 v[246:249], v215
	s_nop 0
	global_load_dwordx4 v[250:253], v[244:245], off
	v_lshl_add_u64 v[254:255], v[164:165], 0, v[190:191]
	s_waitcnt vmcnt(3) lgkmcnt(3)
	v_pk_fma_f32 v[152:153], v[152:153], v[156:157], v[160:161]
	v_pk_fma_f32 v[154:155], v[154:155], v[158:159], v[162:163]
	global_store_dwordx4 v[166:167], v[152:155], off
	s_waitcnt vmcnt(3) lgkmcnt(2)
	v_pk_fma_f32 v[170:171], v[170:171], v[156:157], v[216:217]
	v_pk_fma_f32 v[172:173], v[172:173], v[158:159], v[218:219]
	global_store_dwordx4 v[174:175], v[170:173], off
	s_waitcnt vmcnt(3) lgkmcnt(1)
	v_pk_fma_f32 v[222:223], v[222:223], v[156:157], v[240:241]
	v_pk_fma_f32 v[224:225], v[224:225], v[158:159], v[242:243]
	global_store_dwordx4 v[226:227], v[222:225], off
	s_waitcnt vmcnt(3) lgkmcnt(0)
	v_pk_fma_f32 v[246:247], v[246:247], v[156:157], v[250:251]
	v_pk_fma_f32 v[248:249], v[248:249], v[158:159], v[252:253]
	global_store_dwordx4 v[254:255], v[246:249], off
	s_nop 1
	ds_write_b128 v211, v[48:51]
	ds_write_b128 v211, v[52:55] offset:32
	ds_write_b128 v211, v[56:59] offset:64
	ds_write_b128 v211, v[60:63] offset:96
	ds_read_b128 v[148:151], v212
	global_load_dwordx4 v[152:155], v[128:129], off offset:256
	global_load_dwordx4 v[156:159], v[114:115], off offset:256
	ds_read_b128 v[160:163], v213
	global_load_dwordx4 v[164:167], v[118:119], off offset:256
	ds_read_b128 v[168:171], v214
	global_load_dwordx4 v[172:175], v[122:123], off offset:256
	ds_read_b128 v[216:219], v215
	global_load_dwordx4 v[220:223], v[126:127], off offset:256
	s_waitcnt vmcnt(3) lgkmcnt(3)
	v_pk_fma_f32 v[148:149], v[148:149], v[152:153], v[156:157]
	v_pk_fma_f32 v[150:151], v[150:151], v[154:155], v[158:159]
	global_store_dwordx4 v[112:113], v[148:151], off offset:256
	s_waitcnt vmcnt(3) lgkmcnt(2)
	v_pk_fma_f32 v[160:161], v[160:161], v[152:153], v[164:165]
	v_pk_fma_f32 v[162:163], v[162:163], v[154:155], v[166:167]
	global_store_dwordx4 v[116:117], v[160:163], off offset:256
	s_waitcnt vmcnt(3) lgkmcnt(1)
	v_pk_fma_f32 v[168:169], v[168:169], v[152:153], v[172:173]
	v_pk_fma_f32 v[170:171], v[170:171], v[154:155], v[174:175]
	global_store_dwordx4 v[120:121], v[168:171], off offset:256
	s_waitcnt vmcnt(3) lgkmcnt(0)
	v_pk_fma_f32 v[216:217], v[216:217], v[152:153], v[220:221]
	v_pk_fma_f32 v[218:219], v[218:219], v[154:155], v[222:223]
	global_store_dwordx4 v[124:125], v[216:219], off offset:256
	s_nop 1
	ds_write_b128 v211, v[32:35]
	ds_write_b128 v211, v[36:39] offset:32
	ds_write_b128 v211, v[40:43] offset:64
	ds_write_b128 v211, v[44:47] offset:96
	v_lshl_add_u64 v[148:149], v[130:131], 0, s[54:55]
	v_lshl_add_u64 v[150:151], v[148:149], 0, v[184:185]
	ds_read_b128 v[152:155], v212
	global_load_dwordx4 v[156:159], v[128:129], off offset:256
	s_nop 0
	global_load_dwordx4 v[160:163], v[150:151], off
	v_lshl_add_u64 v[164:165], v[132:133], 0, s[54:55]
	v_lshl_add_u64 v[166:167], v[164:165], 0, v[184:185]
	v_lshl_add_u64 v[168:169], v[148:149], 0, v[186:187]
	ds_read_b128 v[170:173], v213
	s_nop 0
	global_load_dwordx4 v[216:219], v[168:169], off
	v_lshl_add_u64 v[174:175], v[164:165], 0, v[186:187]
	v_lshl_add_u64 v[220:221], v[148:149], 0, v[188:189]
	ds_read_b128 v[222:225], v214
	s_nop 0
	global_load_dwordx4 v[240:243], v[220:221], off
	v_lshl_add_u64 v[226:227], v[164:165], 0, v[188:189]
	v_lshl_add_u64 v[244:245], v[148:149], 0, v[190:191]
	ds_read_b128 v[246:249], v215
	s_nop 0
	global_load_dwordx4 v[250:253], v[244:245], off
	v_lshl_add_u64 v[254:255], v[164:165], 0, v[190:191]
	s_waitcnt vmcnt(3) lgkmcnt(3)
	v_pk_fma_f32 v[152:153], v[152:153], v[156:157], v[160:161]
	v_pk_fma_f32 v[154:155], v[154:155], v[158:159], v[162:163]
	global_store_dwordx4 v[166:167], v[152:155], off
	s_waitcnt vmcnt(3) lgkmcnt(2)
	v_pk_fma_f32 v[170:171], v[170:171], v[156:157], v[216:217]
	v_pk_fma_f32 v[172:173], v[172:173], v[158:159], v[218:219]
	global_store_dwordx4 v[174:175], v[170:173], off
	s_waitcnt vmcnt(3) lgkmcnt(1)
	v_pk_fma_f32 v[222:223], v[222:223], v[156:157], v[240:241]
	v_pk_fma_f32 v[224:225], v[224:225], v[158:159], v[242:243]
	global_store_dwordx4 v[226:227], v[222:225], off
	s_waitcnt vmcnt(3) lgkmcnt(0)
	v_pk_fma_f32 v[246:247], v[246:247], v[156:157], v[250:251]
	v_pk_fma_f32 v[248:249], v[248:249], v[158:159], v[252:253]
	global_store_dwordx4 v[254:255], v[246:249], off
	s_nop 1
	ds_write_b128 v211, v[16:19]
	ds_write_b128 v211, v[20:23] offset:32
	ds_write_b128 v211, v[24:27] offset:64
	ds_write_b128 v211, v[28:31] offset:96
	ds_read_b128 v[148:151], v212
	global_load_dwordx4 v[152:155], v[128:129], off offset:384
	global_load_dwordx4 v[156:159], v[114:115], off offset:384
	ds_read_b128 v[160:163], v213
	global_load_dwordx4 v[164:167], v[118:119], off offset:384
	ds_read_b128 v[168:171], v214
	global_load_dwordx4 v[172:175], v[122:123], off offset:384
	ds_read_b128 v[216:219], v215
	global_load_dwordx4 v[220:223], v[126:127], off offset:384
	s_waitcnt vmcnt(3) lgkmcnt(3)
	v_pk_fma_f32 v[148:149], v[148:149], v[152:153], v[156:157]
	v_pk_fma_f32 v[150:151], v[150:151], v[154:155], v[158:159]
	global_store_dwordx4 v[112:113], v[148:151], off offset:384
	s_waitcnt vmcnt(3) lgkmcnt(2)
	v_pk_fma_f32 v[160:161], v[160:161], v[152:153], v[164:165]
	v_pk_fma_f32 v[162:163], v[162:163], v[154:155], v[166:167]
	global_store_dwordx4 v[116:117], v[160:163], off offset:384
	s_waitcnt vmcnt(3) lgkmcnt(1)
	v_pk_fma_f32 v[168:169], v[168:169], v[152:153], v[172:173]
	v_pk_fma_f32 v[170:171], v[170:171], v[154:155], v[174:175]
	global_store_dwordx4 v[120:121], v[168:171], off offset:384
	s_waitcnt vmcnt(3) lgkmcnt(0)
	v_pk_fma_f32 v[216:217], v[216:217], v[152:153], v[220:221]
	v_pk_fma_f32 v[218:219], v[218:219], v[154:155], v[222:223]
	global_store_dwordx4 v[124:125], v[216:219], off offset:384
	s_nop 1
	ds_write_b128 v211, v[0:3]
	ds_write_b128 v211, v[4:7] offset:32
	ds_write_b128 v211, v[8:11] offset:64
	ds_write_b128 v211, v[12:15] offset:96
	v_lshl_add_u64 v[148:149], v[130:131], 0, s[58:59]
	v_lshl_add_u64 v[150:151], v[148:149], 0, v[184:185]
	ds_read_b128 v[152:155], v212
	global_load_dwordx4 v[156:159], v[128:129], off offset:384
	s_nop 0
	global_load_dwordx4 v[160:163], v[150:151], off
	v_lshl_add_u64 v[164:165], v[132:133], 0, s[58:59]
	v_lshl_add_u64 v[166:167], v[164:165], 0, v[184:185]
	v_lshl_add_u64 v[168:169], v[148:149], 0, v[186:187]
	ds_read_b128 v[170:173], v213
	s_nop 0
	global_load_dwordx4 v[216:219], v[168:169], off
	v_lshl_add_u64 v[174:175], v[164:165], 0, v[186:187]
	v_lshl_add_u64 v[220:221], v[148:149], 0, v[188:189]
	ds_read_b128 v[222:225], v214
	s_nop 0
	global_load_dwordx4 v[240:243], v[220:221], off
	v_lshl_add_u64 v[226:227], v[164:165], 0, v[188:189]
	v_lshl_add_u64 v[244:245], v[148:149], 0, v[190:191]
	ds_read_b128 v[246:249], v215
	s_nop 0
	global_load_dwordx4 v[250:253], v[244:245], off
	v_lshl_add_u64 v[254:255], v[164:165], 0, v[190:191]
	s_waitcnt vmcnt(3) lgkmcnt(3)
	v_pk_fma_f32 v[152:153], v[152:153], v[156:157], v[160:161]
	v_pk_fma_f32 v[154:155], v[154:155], v[158:159], v[162:163]
	global_store_dwordx4 v[166:167], v[152:155], off
	s_waitcnt vmcnt(3) lgkmcnt(2)
	v_pk_fma_f32 v[170:171], v[170:171], v[156:157], v[216:217]
	v_pk_fma_f32 v[172:173], v[172:173], v[158:159], v[218:219]
	global_store_dwordx4 v[174:175], v[170:173], off
	s_waitcnt vmcnt(3) lgkmcnt(1)
	v_pk_fma_f32 v[222:223], v[222:223], v[156:157], v[240:241]
	v_pk_fma_f32 v[224:225], v[224:225], v[158:159], v[242:243]
	global_store_dwordx4 v[226:227], v[222:225], off
	s_waitcnt vmcnt(3) lgkmcnt(0)
	v_pk_fma_f32 v[246:247], v[246:247], v[156:157], v[250:251]
	v_pk_fma_f32 v[248:249], v[248:249], v[158:159], v[252:253]
	global_store_dwordx4 v[254:255], v[246:249], off
	s_nop 1
	s_barrier
	s_cbranch_scc1 .LBB0_434

.LBB0_732:
	s_lshl_b32 s24, s31, 8
	s_add_i32 s54, s24, s37
	s_lshl_b64 s[2:3], s[2:3], s60
	s_lshl_b64 s[58:59], s[58:59], 12
	s_add_u32 s24, s56, s58
	s_addc_u32 s55, s57, s59
	s_lshl_b64 s[2:3], s[2:3], 2
	s_add_u32 s24, s24, s2
	s_addc_u32 s56, s55, s3
	s_ashr_i32 s55, s54, 31
	s_lshl_b64 s[2:3], s[54:55], 2
	s_add_u32 s54, s24, s2
	s_addc_u32 s55, s56, s3
	s_add_u32 s24, s20, s52
	s_addc_u32 s52, s21, s53
	s_add_u32 s2, s24, s2
	s_addc_u32 s3, s52, s3
	s_waitcnt lgkmcnt(5)
	v_lshl_add_u64 v[138:139], s[2:3], 0, v[178:179]
	s_mov_b64 s[2:3], 0x5000
	s_waitcnt lgkmcnt(4)
	v_lshl_add_u64 v[128:129], v[138:139], 0, s[2:3]
	s_movk_i32 s2, 0x5000
	s_waitcnt lgkmcnt(0)
	v_add_co_u32_e32 v136, vcc, s2, v138
	v_lshl_add_u64 v[130:131], s[54:55], 0, v[178:179]
	ds_write_b128 v211, v[112:115]
	ds_write_b128 v211, v[116:119] offset:32
	ds_write_b128 v211, v[120:123] offset:64
	ds_write_b128 v211, v[124:127] offset:96
	v_mov_b32_e32 v185, v179
	v_addc_co_u32_e32 v137, vcc, 0, v139, vcc
	v_lshl_add_u64 v[112:113], v[130:131], 0, v[184:185]
	ds_read_b128 v[140:143], v212
	global_load_dwordx4 v[144:147], v[136:137], off
	global_load_dwordx4 v[148:151], v[112:113], off
	v_mov_b32_e32 v187, v179
	v_mov_b32_e32 v189, v179
	v_mov_b32_e32 v191, v179
	s_mov_b64 s[2:3], 0x20000
	s_add_i32 s70, s70, 1
	s_cmp_eq_u32 s70, s35
	v_lshl_add_u64 v[118:119], v[130:131], 0, v[186:187]
	ds_read_b128 v[152:155], v213
	global_load_dwordx4 v[156:159], v[118:119], off
	ds_read_b128 v[160:163], v214
	s_nop 0
	v_lshl_add_u64 v[116:117], v[130:131], 0, v[188:189]
	global_load_dwordx4 v[164:167], v[116:117], off
	v_lshl_add_u64 v[114:115], v[130:131], 0, v[190:191]
	ds_read_b128 v[168:171], v215
	global_load_dwordx4 v[172:175], v[114:115], off
	s_waitcnt vmcnt(3) lgkmcnt(3)
	v_pk_fma_f32 v[140:141], v[140:141], v[144:145], v[148:149]
	v_pk_fma_f32 v[142:143], v[142:143], v[146:147], v[150:151]
	global_store_dwordx4 v[112:113], v[140:143], off
	s_waitcnt vmcnt(3) lgkmcnt(2)
	v_pk_fma_f32 v[152:153], v[152:153], v[144:145], v[156:157]
	v_pk_fma_f32 v[154:155], v[154:155], v[146:147], v[158:159]
	global_store_dwordx4 v[118:119], v[152:155], off
	s_waitcnt vmcnt(3) lgkmcnt(1)
	v_pk_fma_f32 v[160:161], v[160:161], v[144:145], v[164:165]
	v_pk_fma_f32 v[162:163], v[162:163], v[146:147], v[166:167]
	global_store_dwordx4 v[116:117], v[160:163], off
	s_waitcnt vmcnt(3) lgkmcnt(0)
	v_pk_fma_f32 v[168:169], v[168:169], v[144:145], v[172:173]
	v_pk_fma_f32 v[170:171], v[170:171], v[146:147], v[174:175]
	global_store_dwordx4 v[114:115], v[168:171], off
	s_nop 1
	ds_write_b128 v211, v[96:99]
	ds_write_b128 v211, v[100:103] offset:32
	ds_write_b128 v211, v[104:107] offset:64
	ds_write_b128 v211, v[108:111] offset:96
	v_lshl_add_u64 v[138:139], v[130:131], 0, s[2:3]
	v_lshl_add_u64 v[140:141], v[138:139], 0, v[184:185]
	ds_read_b128 v[142:145], v212
	global_load_dwordx4 v[146:149], v[136:137], off
	global_load_dwordx4 v[150:153], v[140:141], off
	s_mov_b64 s[2:3], 0x20080
	v_lshl_add_u64 v[154:155], v[138:139], 0, v[186:187]
	ds_read_b128 v[156:159], v213
	global_load_dwordx4 v[160:163], v[154:155], off
	v_lshl_add_u64 v[164:165], v[138:139], 0, v[188:189]
	ds_read_b128 v[166:169], v214
	global_load_dwordx4 v[170:173], v[164:165], off
	v_lshl_add_u64 v[174:175], v[138:139], 0, v[190:191]
	ds_read_b128 v[216:219], v215
	global_load_dwordx4 v[220:223], v[174:175], off
	s_waitcnt vmcnt(3) lgkmcnt(3)
	v_pk_fma_f32 v[142:143], v[142:143], v[146:147], v[150:151]
	v_pk_fma_f32 v[144:145], v[144:145], v[148:149], v[152:153]
	global_store_dwordx4 v[140:141], v[142:145], off
	s_waitcnt vmcnt(3) lgkmcnt(2)
	v_pk_fma_f32 v[156:157], v[156:157], v[146:147], v[160:161]
	v_pk_fma_f32 v[158:159], v[158:159], v[148:149], v[162:163]
	global_store_dwordx4 v[154:155], v[156:159], off
	s_waitcnt vmcnt(3) lgkmcnt(1)
	v_pk_fma_f32 v[166:167], v[166:167], v[146:147], v[170:171]
	v_pk_fma_f32 v[168:169], v[168:169], v[148:149], v[172:173]
	global_store_dwordx4 v[164:165], v[166:169], off
	s_waitcnt vmcnt(3) lgkmcnt(0)
	v_pk_fma_f32 v[216:217], v[216:217], v[146:147], v[220:221]
	v_pk_fma_f32 v[218:219], v[218:219], v[148:149], v[222:223]
	global_store_dwordx4 v[174:175], v[216:219], off
	s_nop 1
	ds_write_b128 v211, v[80:83]
	ds_write_b128 v211, v[84:87] offset:32
	ds_write_b128 v211, v[88:91] offset:64
	ds_write_b128 v211, v[92:95] offset:96
	ds_read_b128 v[138:141], v212
	global_load_dwordx4 v[142:145], v[128:129], off offset:128
	global_load_dwordx4 v[146:149], v[112:113], off offset:128
	ds_read_b128 v[150:153], v213
	global_load_dwordx4 v[154:157], v[118:119], off offset:128
	ds_read_b128 v[158:161], v214
	global_load_dwordx4 v[162:165], v[116:117], off offset:128
	ds_read_b128 v[166:169], v215
	global_load_dwordx4 v[170:173], v[114:115], off offset:128
	s_waitcnt vmcnt(3) lgkmcnt(3)
	v_pk_fma_f32 v[138:139], v[138:139], v[142:143], v[146:147]
	v_pk_fma_f32 v[140:141], v[140:141], v[144:145], v[148:149]
	global_store_dwordx4 v[112:113], v[138:141], off offset:128
	s_waitcnt vmcnt(3) lgkmcnt(2)
	v_pk_fma_f32 v[150:151], v[150:151], v[142:143], v[154:155]
	v_pk_fma_f32 v[152:153], v[152:153], v[144:145], v[156:157]
	global_store_dwordx4 v[118:119], v[150:153], off offset:128
	s_waitcnt vmcnt(3) lgkmcnt(1)
	v_pk_fma_f32 v[158:159], v[158:159], v[142:143], v[162:163]
	v_pk_fma_f32 v[160:161], v[160:161], v[144:145], v[164:165]
	global_store_dwordx4 v[116:117], v[158:161], off offset:128
	s_waitcnt vmcnt(3) lgkmcnt(0)
	v_pk_fma_f32 v[166:167], v[166:167], v[142:143], v[170:171]
	v_pk_fma_f32 v[168:169], v[168:169], v[144:145], v[172:173]
	global_store_dwordx4 v[114:115], v[166:169], off offset:128
	s_nop 1
	ds_write_b128 v211, v[64:67]
	ds_write_b128 v211, v[68:71] offset:32
	ds_write_b128 v211, v[72:75] offset:64
	ds_write_b128 v211, v[76:79] offset:96
	v_lshl_add_u64 v[138:139], v[130:131], 0, s[2:3]
	v_lshl_add_u64 v[140:141], v[138:139], 0, v[184:185]
	ds_read_b128 v[142:145], v212
	global_load_dwordx4 v[146:149], v[128:129], off offset:128
	global_load_dwordx4 v[150:153], v[140:141], off
	s_mov_b64 s[2:3], 0x20100
	v_lshl_add_u64 v[154:155], v[138:139], 0, v[186:187]
	ds_read_b128 v[156:159], v213
	global_load_dwordx4 v[160:163], v[154:155], off
	v_lshl_add_u64 v[164:165], v[138:139], 0, v[188:189]
	ds_read_b128 v[166:169], v214
	global_load_dwordx4 v[170:173], v[164:165], off
	v_lshl_add_u64 v[174:175], v[138:139], 0, v[190:191]
	ds_read_b128 v[216:219], v215
	global_load_dwordx4 v[220:223], v[174:175], off
	s_waitcnt vmcnt(3) lgkmcnt(3)
	v_pk_fma_f32 v[142:143], v[142:143], v[146:147], v[150:151]
	v_pk_fma_f32 v[144:145], v[144:145], v[148:149], v[152:153]
	global_store_dwordx4 v[140:141], v[142:145], off
	s_waitcnt vmcnt(3) lgkmcnt(2)
	v_pk_fma_f32 v[156:157], v[156:157], v[146:147], v[160:161]
	v_pk_fma_f32 v[158:159], v[158:159], v[148:149], v[162:163]
	global_store_dwordx4 v[154:155], v[156:159], off
	s_waitcnt vmcnt(3) lgkmcnt(1)
	v_pk_fma_f32 v[166:167], v[166:167], v[146:147], v[170:171]
	v_pk_fma_f32 v[168:169], v[168:169], v[148:149], v[172:173]
	global_store_dwordx4 v[164:165], v[166:169], off
	s_waitcnt vmcnt(3) lgkmcnt(0)
	v_pk_fma_f32 v[216:217], v[216:217], v[146:147], v[220:221]
	v_pk_fma_f32 v[218:219], v[218:219], v[148:149], v[222:223]
	global_store_dwordx4 v[174:175], v[216:219], off
	s_nop 1
	ds_write_b128 v211, v[48:51]
	ds_write_b128 v211, v[52:55] offset:32
	ds_write_b128 v211, v[56:59] offset:64
	ds_write_b128 v211, v[60:63] offset:96
	ds_read_b128 v[138:141], v212
	global_load_dwordx4 v[142:145], v[128:129], off offset:256
	global_load_dwordx4 v[146:149], v[112:113], off offset:256
	ds_read_b128 v[150:153], v213
	global_load_dwordx4 v[154:157], v[118:119], off offset:256
	ds_read_b128 v[158:161], v214
	global_load_dwordx4 v[162:165], v[116:117], off offset:256
	ds_read_b128 v[166:169], v215
	global_load_dwordx4 v[170:173], v[114:115], off offset:256
	s_waitcnt vmcnt(3) lgkmcnt(3)
	v_pk_fma_f32 v[138:139], v[138:139], v[142:143], v[146:147]
	v_pk_fma_f32 v[140:141], v[140:141], v[144:145], v[148:149]
	global_store_dwordx4 v[112:113], v[138:141], off offset:256
	s_waitcnt vmcnt(3) lgkmcnt(2)
	v_pk_fma_f32 v[150:151], v[150:151], v[142:143], v[154:155]
	v_pk_fma_f32 v[152:153], v[152:153], v[144:145], v[156:157]
	global_store_dwordx4 v[118:119], v[150:153], off offset:256
	s_waitcnt vmcnt(3) lgkmcnt(1)
	v_pk_fma_f32 v[158:159], v[158:159], v[142:143], v[162:163]
	v_pk_fma_f32 v[160:161], v[160:161], v[144:145], v[164:165]
	global_store_dwordx4 v[116:117], v[158:161], off offset:256
	s_waitcnt vmcnt(3) lgkmcnt(0)
	v_pk_fma_f32 v[166:167], v[166:167], v[142:143], v[170:171]
	v_pk_fma_f32 v[168:169], v[168:169], v[144:145], v[172:173]
	global_store_dwordx4 v[114:115], v[166:169], off offset:256
	s_nop 1
	ds_write_b128 v211, v[32:35]
	ds_write_b128 v211, v[36:39] offset:32
	ds_write_b128 v211, v[40:43] offset:64
	ds_write_b128 v211, v[44:47] offset:96
	v_lshl_add_u64 v[138:139], v[130:131], 0, s[2:3]
	v_lshl_add_u64 v[140:141], v[138:139], 0, v[184:185]
	ds_read_b128 v[142:145], v212
	global_load_dwordx4 v[146:149], v[128:129], off offset:256
	global_load_dwordx4 v[150:153], v[140:141], off
	s_mov_b64 s[2:3], 0x20180
	v_lshl_add_u64 v[154:155], v[138:139], 0, v[186:187]
	ds_read_b128 v[156:159], v213
	global_load_dwordx4 v[160:163], v[154:155], off
	v_lshl_add_u64 v[164:165], v[138:139], 0, v[188:189]
	ds_read_b128 v[166:169], v214
	global_load_dwordx4 v[170:173], v[164:165], off
	v_lshl_add_u64 v[174:175], v[138:139], 0, v[190:191]
	ds_read_b128 v[216:219], v215
	global_load_dwordx4 v[220:223], v[174:175], off
	s_waitcnt vmcnt(3) lgkmcnt(3)
	v_pk_fma_f32 v[142:143], v[142:143], v[146:147], v[150:151]
	v_pk_fma_f32 v[144:145], v[144:145], v[148:149], v[152:153]
	global_store_dwordx4 v[140:141], v[142:145], off
	s_waitcnt vmcnt(3) lgkmcnt(2)
	v_pk_fma_f32 v[156:157], v[156:157], v[146:147], v[160:161]
	v_pk_fma_f32 v[158:159], v[158:159], v[148:149], v[162:163]
	global_store_dwordx4 v[154:155], v[156:159], off
	s_waitcnt vmcnt(3) lgkmcnt(1)
	v_pk_fma_f32 v[166:167], v[166:167], v[146:147], v[170:171]
	v_pk_fma_f32 v[168:169], v[168:169], v[148:149], v[172:173]
	global_store_dwordx4 v[164:165], v[166:169], off
	s_waitcnt vmcnt(3) lgkmcnt(0)
	v_pk_fma_f32 v[216:217], v[216:217], v[146:147], v[220:221]
	v_pk_fma_f32 v[218:219], v[218:219], v[148:149], v[222:223]
	global_store_dwordx4 v[174:175], v[216:219], off
	s_nop 1
	ds_write_b128 v211, v[16:19]
	ds_write_b128 v211, v[20:23] offset:32
	ds_write_b128 v211, v[24:27] offset:64
	ds_write_b128 v211, v[28:31] offset:96
	ds_read_b128 v[138:141], v212
	global_load_dwordx4 v[142:145], v[128:129], off offset:384
	global_load_dwordx4 v[146:149], v[112:113], off offset:384
	ds_read_b128 v[150:153], v213
	global_load_dwordx4 v[154:157], v[118:119], off offset:384
	ds_read_b128 v[158:161], v214
	global_load_dwordx4 v[162:165], v[116:117], off offset:384
	ds_read_b128 v[166:169], v215
	global_load_dwordx4 v[170:173], v[114:115], off offset:384
	s_waitcnt vmcnt(3) lgkmcnt(3)
	v_pk_fma_f32 v[138:139], v[138:139], v[142:143], v[146:147]
	v_pk_fma_f32 v[140:141], v[140:141], v[144:145], v[148:149]
	global_store_dwordx4 v[112:113], v[138:141], off offset:384
	s_waitcnt vmcnt(3) lgkmcnt(2)
	v_pk_fma_f32 v[150:151], v[150:151], v[142:143], v[154:155]
	v_pk_fma_f32 v[152:153], v[152:153], v[144:145], v[156:157]
	global_store_dwordx4 v[118:119], v[150:153], off offset:384
	s_waitcnt vmcnt(3) lgkmcnt(1)
	v_pk_fma_f32 v[158:159], v[158:159], v[142:143], v[162:163]
	v_pk_fma_f32 v[160:161], v[160:161], v[144:145], v[164:165]
	global_store_dwordx4 v[116:117], v[158:161], off offset:384
	s_waitcnt vmcnt(3) lgkmcnt(0)
	v_pk_fma_f32 v[166:167], v[166:167], v[142:143], v[170:171]
	v_pk_fma_f32 v[168:169], v[168:169], v[144:145], v[172:173]
	global_store_dwordx4 v[114:115], v[166:169], off offset:384
	s_nop 1
	ds_write_b128 v211, v[0:3]
	ds_write_b128 v211, v[4:7] offset:32
	ds_write_b128 v211, v[8:11] offset:64
	ds_write_b128 v211, v[12:15] offset:96
	v_lshl_add_u64 v[138:139], v[130:131], 0, s[2:3]
	v_lshl_add_u64 v[140:141], v[138:139], 0, v[184:185]
	ds_read_b128 v[142:145], v212
	global_load_dwordx4 v[146:149], v[128:129], off offset:384
	global_load_dwordx4 v[150:153], v[140:141], off
	v_lshl_add_u64 v[154:155], v[138:139], 0, v[186:187]
	ds_read_b128 v[156:159], v213
	global_load_dwordx4 v[160:163], v[154:155], off
	v_lshl_add_u64 v[164:165], v[138:139], 0, v[188:189]
	ds_read_b128 v[166:169], v214
	global_load_dwordx4 v[170:173], v[164:165], off
	v_lshl_add_u64 v[174:175], v[138:139], 0, v[190:191]
	ds_read_b128 v[216:219], v215
	global_load_dwordx4 v[220:223], v[174:175], off
	s_waitcnt vmcnt(3) lgkmcnt(3)
	v_pk_fma_f32 v[142:143], v[142:143], v[146:147], v[150:151]
	v_pk_fma_f32 v[144:145], v[144:145], v[148:149], v[152:153]
	global_store_dwordx4 v[140:141], v[142:145], off
	s_waitcnt vmcnt(3) lgkmcnt(2)
	v_pk_fma_f32 v[156:157], v[156:157], v[146:147], v[160:161]
	v_pk_fma_f32 v[158:159], v[158:159], v[148:149], v[162:163]
	global_store_dwordx4 v[154:155], v[156:159], off
	s_waitcnt vmcnt(3) lgkmcnt(1)
	v_pk_fma_f32 v[166:167], v[166:167], v[146:147], v[170:171]
	v_pk_fma_f32 v[168:169], v[168:169], v[148:149], v[172:173]
	global_store_dwordx4 v[164:165], v[166:169], off
	s_waitcnt vmcnt(3) lgkmcnt(0)
	v_pk_fma_f32 v[216:217], v[216:217], v[146:147], v[220:221]
	v_pk_fma_f32 v[218:219], v[218:219], v[148:149], v[222:223]
	global_store_dwordx4 v[174:175], v[216:219], off
	s_nop 1
	s_barrier
	s_cbranch_scc1 .LBB0_788

	.amdhsa_kernel _Z14fwd_megakernel6Paramsii
		.amdhsa_group_segment_fixed_size 143376
		.amdhsa_private_segment_fixed_size 0
		.amdhsa_kernarg_size 560
		.amdhsa_user_sgpr_count 2
		.amdhsa_user_sgpr_dispatch_ptr 0
		.amdhsa_user_sgpr_queue_ptr 0
		.amdhsa_user_sgpr_kernarg_segment_ptr 1
		.amdhsa_user_sgpr_dispatch_id 0
		.amdhsa_user_sgpr_kernarg_preload_length 0
		.amdhsa_user_sgpr_kernarg_preload_offset 0
		.amdhsa_user_sgpr_private_segment_size 0
		.amdhsa_uses_dynamic_stack 0
		.amdhsa_enable_private_segment 0
		.amdhsa_system_sgpr_workgroup_id_x 1
		.amdhsa_system_sgpr_workgroup_id_y 0
		.amdhsa_system_sgpr_workgroup_id_z 0
		.amdhsa_system_sgpr_workgroup_info 0
		.amdhsa_system_vgpr_workitem_id 2
		.amdhsa_next_free_vgpr 256
		.amdhsa_next_free_sgpr 98
		.amdhsa_accum_offset 256
		.amdhsa_reserve_vcc 1
		.amdhsa_float_round_mode_32 0
		.amdhsa_float_round_mode_16_64 0
		.amdhsa_float_denorm_mode_32 3
		.amdhsa_float_denorm_mode_16_64 3
		.amdhsa_dx10_clamp 1
		.amdhsa_ieee_mode 1
		.amdhsa_fp16_overflow 0
		.amdhsa_tg_split 0
		.amdhsa_exception_fp_ieee_invalid_op 0
		.amdhsa_exception_fp_denorm_src 0
		.amdhsa_exception_fp_ieee_div_zero 0
		.amdhsa_exception_fp_ieee_overflow 0
		.amdhsa_exception_fp_ieee_underflow 0
		.amdhsa_exception_fp_ieee_inexact 0
		.amdhsa_exception_int_div_zero 0
	.end_amdhsa_kernel

amdhsa.kernels:
  - .agpr_count:     0
    .args:
      - .offset:         0
        .size:           296
        .value_kind:     by_value
      - .offset:         296
        .size:           4
        .value_kind:     by_value
      - .offset:         300
        .size:           4
        .value_kind:     by_value
      - .offset:         304
        .size:           4
        .value_kind:     hidden_block_count_x
      - .offset:         308
        .size:           4
        .value_kind:     hidden_block_count_y
      - .offset:         312
        .size:           4
        .value_kind:     hidden_block_count_z
      - .offset:         316
        .size:           2
        .value_kind:     hidden_group_size_x
      - .offset:         318
        .size:           2
        .value_kind:     hidden_group_size_y
      - .offset:         320
        .size:           2
        .value_kind:     hidden_group_size_z
      - .offset:         322
        .size:           2
        .value_kind:     hidden_remainder_x
      - .offset:         324
        .size:           2
        .value_kind:     hidden_remainder_y
      - .offset:         326
        .size:           2
        .value_kind:     hidden_remainder_z
      - .offset:         344
        .size:           8
        .value_kind:     hidden_global_offset_x
      - .offset:         352
        .size:           8
        .value_kind:     hidden_global_offset_y
      - .offset:         360
        .size:           8
        .value_kind:     hidden_global_offset_z
      - .offset:         368
        .size:           2
        .value_kind:     hidden_grid_dims
      - .offset:         392
        .size:           8
        .value_kind:     hidden_multigrid_sync_arg
    .group_segment_fixed_size: 143376
    .kernarg_segment_align: 8
    .kernarg_segment_size: 560
    .language:       OpenCL C
    .language_version:
      - 2
      - 0
    .max_flat_workgroup_size: 512
    .name:           _Z14fwd_megakernel6Paramsii
    .private_segment_fixed_size: 0
    .sgpr_count:     104
    .sgpr_spill_count: 65
    .symbol:         _Z14fwd_megakernel6Paramsii.kd
    .uniform_work_group_size: 1
    .uses_dynamic_stack: false
    .vgpr_count:     256
    .vgpr_spill_count: 0
    .wavefront_size: 64
